# prompt conv LN token loop: the token's two cz loads issued at the top of the iteration (overlap LDS reads and reductions)
# baseline (speedup 1.0000x reference)
.LBB0_635:
	v_lshl_add_u64 v[234:235], s[14:15], 0, v[20:21]
	v_add_co_u32_e32 v234, vcc, 0x19b03000, v234
	s_nop 1
	v_addc_co_u32_e32 v235, vcc, 0, v235, vcc
	global_load_dwordx4 v[54:57], v[234:235], off offset:2048
	global_load_dwordx4 v[230:233], v[234:235], off offset:3072
	ds_read_b128 v[14:17], v40
	ds_read_b128 v[10:13], v40 offset:16
	ds_read_b128 v[6:9], v40 offset:2048
	s_waitcnt lgkmcnt(2)
	v_mov_b32_e32 v2, v15
	v_mov_b32_e32 v3, v16
	v_mov_b32_e32 v4, v14
	v_mov_b32_e32 v5, v17
	v_pk_add_f32 v[2:3], v[2:3], v[4:5]
	s_waitcnt lgkmcnt(1)
	v_mov_b32_e32 v4, v10
	v_add_f32_e32 v2, v2, v3
	v_add_f32_e32 v28, 0, v2
	v_mov_b32_e32 v2, v11
	v_mov_b32_e32 v3, v12
	v_mov_b32_e32 v5, v13
	v_pk_add_f32 v[2:3], v[2:3], v[4:5]
	s_nop 0
	v_pk_add_f32 v[30:31], v[2:3], v[2:3] op_sel:[0,1] op_sel_hi:[1,0]
	ds_read_b128 v[2:5], v40 offset:2064
	s_waitcnt lgkmcnt(1)
	v_add_f32_e32 v32, v6, v7
	v_add_f32_e32 v42, v8, v9
	v_add_u32_e32 v40, 0x8000, v40
	s_waitcnt lgkmcnt(0)
	v_mov_b32_e32 v29, v2
	v_mov_b32_e32 v31, v3
	v_mov_b32_e32 v33, v4
	v_mov_b32_e32 v43, v5
	v_pk_add_f32 v[28:29], v[28:29], v[30:31]
	v_pk_add_f32 v[30:31], v[32:33], v[42:43]
	s_nop 0
	v_pk_add_f32 v[28:29], v[28:29], v[30:31]
	s_nop 0
	v_add_f32_e32 v26, v28, v29
	s_waitcnt lgkmcnt(0)
	s_nop 1
	v_add_f32_dpp v26, v26, v26 quad_perm:[1,0,3,2] row_mask:0xf bank_mask:0xf
	s_nop 1
	v_add_f32_dpp v26, v26, v26 quad_perm:[2,3,0,1] row_mask:0xf bank_mask:0xf
	s_nop 1
	v_add_f32_dpp v26, v26, v26 row_half_mirror row_mask:0xf bank_mask:0xf
	s_nop 1
	v_add_f32_dpp v26, v26, v26 row_mirror row_mask:0xf bank_mask:0xf
	s_nop 1
	v_add_f32_dpp v26, v26, v26 row_bcast:15 row_mask:0xa bank_mask:0xf
	s_nop 1
	v_add_f32_dpp v26, v26, v26 row_bcast:31 row_mask:0xc bank_mask:0xf
	s_nop 1
	v_readlane_b32 s100, v26, 63
	v_mov_b32_e32 v26, s100
	v_fmamk_f32 v33, v26, 0xba800000, v15
	v_fmamk_f32 v32, v26, 0xba800000, v14
	v_fmamk_f32 v17, v26, 0xba800000, v17
	v_fmac_f32_e32 v16, 0xba800000, v26
	v_pk_mul_f32 v[14:15], v[16:17], v[16:17]
	v_pk_mul_f32 v[28:29], v[32:33], v[32:33]
	v_fmamk_f32 v13, v26, 0xba800000, v13
	v_pk_mov_b32 v[30:31], v[28:29], v[14:15] op_sel:[1,0]
	v_mov_b32_e32 v29, v15
	v_pk_add_f32 v[14:15], v[30:31], v[28:29]
	v_fmamk_f32 v31, v26, 0xba800000, v11
	v_fmamk_f32 v30, v26, 0xba800000, v10
	v_fmac_f32_e32 v12, 0xba800000, v26
	v_pk_add_f32 v[28:29], v[14:15], v[14:15] op_sel_hi:[0,1]
	v_pk_mul_f32 v[10:11], v[12:13], v[12:13]
	v_pk_mul_f32 v[14:15], v[30:31], v[30:31]
	v_fmac_f32_e32 v8, 0xba800000, v26
	v_pk_mov_b32 v[42:43], v[14:15], v[10:11] op_sel:[1,0]
	v_mov_b32_e32 v15, v11
	v_pk_add_f32 v[10:11], v[42:43], v[14:15]
	v_fmamk_f32 v14, v26, 0xba800000, v6
	v_fmamk_f32 v15, v26, 0xba800000, v7
	v_mul_f32_e32 v6, v14, v14
	v_pk_fma_f32 v[6:7], v[14:15], v[14:15], v[6:7] op_sel_hi:[1,1,0]
	v_fmamk_f32 v9, v26, 0xba800000, v9
	v_mul_f32_e32 v6, v8, v8
	v_pk_add_f32 v[42:43], v[10:11], v[10:11] op_sel_hi:[0,1]
	v_pk_fma_f32 v[44:45], v[8:9], v[8:9], v[6:7] op_sel_hi:[1,1,0]
	v_fmamk_f32 v11, v26, 0xba800000, v5
	v_fmamk_f32 v10, v26, 0xba800000, v4
	v_fmamk_f32 v3, v26, 0xba800000, v3
	v_fmac_f32_e32 v2, 0xba800000, v26
	v_mul_f32_e32 v6, v2, v2
	v_mul_f32_e32 v44, v3, v3
	v_mul_f32_e32 v28, v10, v10
	v_mul_f32_e32 v42, v11, v11
	v_pk_add_f32 v[4:5], v[6:7], v[44:45]
	v_pk_add_f32 v[6:7], v[28:29], v[42:43]
	s_nop 0
	v_pk_add_f32 v[4:5], v[4:5], v[6:7]
	s_nop 0
	v_add_f32_e32 v4, v4, v5
	s_waitcnt lgkmcnt(0)
	s_nop 1
	v_add_f32_dpp v4, v4, v4 quad_perm:[1,0,3,2] row_mask:0xf bank_mask:0xf
	s_nop 1
	v_add_f32_dpp v4, v4, v4 quad_perm:[2,3,0,1] row_mask:0xf bank_mask:0xf
	s_nop 1
	v_add_f32_dpp v4, v4, v4 row_half_mirror row_mask:0xf bank_mask:0xf
	s_nop 1
	v_add_f32_dpp v4, v4, v4 row_mirror row_mask:0xf bank_mask:0xf
	s_nop 1
	v_add_f32_dpp v4, v4, v4 row_bcast:15 row_mask:0xa bank_mask:0xf
	s_nop 1
	v_add_f32_dpp v4, v4, v4 row_bcast:31 row_mask:0xc bank_mask:0xf
	s_nop 1
	v_readlane_b32 s100, v4, 63
	v_mov_b32_e32 v4, s100
	v_fmamk_f32 v4, v4, 0x3a800000, v171
	v_cmp_gt_f32_e32 vcc, s9, v4
	v_mul_f32_e32 v5, 0x4f800000, v4
	s_nop 0
	v_cndmask_b32_e32 v4, v4, v5, vcc
	v_sqrt_f32_e32 v5, v4
	s_nop 0
	v_add_u32_e32 v6, -1, v5
	v_fma_f32 v7, -v6, v5, v4
	v_cmp_ge_f32_e64 s[0:1], 0, v7
	v_add_u32_e32 v7, 1, v5
	s_nop 0
	v_cndmask_b32_e64 v6, v5, v6, s[0:1]
	v_fma_f32 v5, -v7, v5, v4
	v_cmp_lt_f32_e64 s[0:1], 0, v5
	s_nop 1
	v_cndmask_b32_e64 v5, v6, v7, s[0:1]
	v_mul_f32_e32 v6, 0x37800000, v5
	v_cndmask_b32_e32 v5, v5, v6, vcc
	v_cmp_class_f32_e32 vcc, v4, v200
	s_nop 1
	v_cndmask_b32_e32 v4, v5, v4, vcc
	v_div_scale_f32 v5, s[0:1], v4, v4, 1.0
	v_rcp_f32_e32 v6, v5
	s_mov_b32 s0, 0x19b03000
	v_fma_f32 v7, -v5, v6, 1.0
	v_fmac_f32_e32 v6, v7, v6
	v_div_scale_f32 v7, vcc, 1.0, v4, 1.0
	v_mul_f32_e32 v26, v7, v6
	v_fma_f32 v28, -v5, v26, v7
	v_fmac_f32_e32 v26, v28, v6
	v_fma_f32 v5, -v5, v26, v7
	v_div_fmas_f32 v5, v5, v6, v26
	v_div_fixup_f32 v26, v5, v4, 1.0
	flat_load_dwordx4 v[4:7], v[22:23]
	flat_load_dwordx4 v[42:45], v[22:23] offset:16
	flat_load_dwordx4 v[46:49], v[24:25]
	flat_load_dwordx4 v[50:53], v[24:25] offset:16
	v_lshl_add_u64 v[28:29], s[14:15], 0, v[20:21]
	v_add_co_u32_e32 v28, vcc, s0, v28
	v_pk_mul_f32 v[32:33], v[32:33], v[26:27] op_sel_hi:[1,0]
	s_nop 0
	v_addc_co_u32_e32 v29, vcc, 0, v29, vcc
	s_nop 0
	global_load_dwordx4 v[214:217], v[22:23], off offset:2048
	global_load_dwordx4 v[218:221], v[22:23], off offset:2064
	global_load_dwordx4 v[222:225], v[24:25], off offset:2048
	global_load_dwordx4 v[226:229], v[24:25], off offset:2064
	s_nop 0
	v_pk_mul_f32 v[16:17], v[16:17], v[26:27] op_sel_hi:[1,0]
	v_pk_mul_f32 v[12:13], v[12:13], v[26:27] op_sel_hi:[1,0]
	s_mov_b32 s0, 0x2ce00000
	v_pk_mul_f32 v[14:15], v[14:15], v[26:27] op_sel_hi:[1,0]
	v_pk_mul_f32 v[8:9], v[8:9], v[26:27] op_sel_hi:[1,0]
	v_pk_mul_f32 v[2:3], v[2:3], v[26:27] op_sel_hi:[1,0]
	s_waitcnt vmcnt(0) lgkmcnt(0)
	v_pk_fma_f32 v[4:5], v[4:5], v[32:33], v[46:47]
	v_pk_fma_f32 v[6:7], v[6:7], v[16:17], v[48:49]
	v_mul_f32_e32 v16, 0xbfb8aa3b, v4
	v_mul_f32_e32 v17, 0xbfb8aa3b, v5
	v_exp_f32_e32 v16, v16
	v_exp_f32_e32 v17, v17
	v_mul_f32_e32 v32, 0xbfb8aa3b, v6
	v_mul_f32_e32 v33, 0xbfb8aa3b, v7
	v_exp_f32_e32 v32, v32
	v_exp_f32_e32 v33, v33
	v_add_f32_e32 v16, 1.0, v16
	v_add_f32_e32 v17, 1.0, v17
	v_rcp_f32_e32 v16, v16
	v_rcp_f32_e32 v17, v17
	v_add_f32_e32 v32, 1.0, v32
	v_add_f32_e32 v33, 1.0, v33
	v_rcp_f32_e32 v32, v32
	v_rcp_f32_e32 v33, v33
	v_pk_mul_f32 v[4:5], v[4:5], v[16:17]
	v_pk_mul_f32 v[16:17], v[30:31], v[26:27] op_sel_hi:[1,0]
	v_pk_fma_f32 v[12:13], v[44:45], v[12:13], v[52:53]
	v_pk_mul_f32 v[6:7], v[6:7], v[32:33]
	v_pk_fma_f32 v[16:17], v[42:43], v[16:17], v[50:51]
	v_mul_f32_e32 v32, 0xbfb8aa3b, v12
	v_mul_f32_e32 v33, 0xbfb8aa3b, v13
	v_mul_f32_e32 v30, 0xbfb8aa3b, v16
	v_mul_f32_e32 v31, 0xbfb8aa3b, v17
	v_exp_f32_e32 v32, v32
	v_exp_f32_e32 v33, v33
	v_exp_f32_e32 v30, v30
	v_exp_f32_e32 v31, v31
	v_add_f32_e32 v32, 1.0, v32
	v_add_f32_e32 v33, 1.0, v33
	v_add_f32_e32 v30, 1.0, v30
	v_add_f32_e32 v31, 1.0, v31
	v_rcp_f32_e32 v32, v32
	v_rcp_f32_e32 v33, v33
	v_rcp_f32_e32 v30, v30
	v_rcp_f32_e32 v31, v31
	v_lshlrev_b32_e32 v58, 16, v54
	v_and_b32_e32 v59, 0xffff0000, v54
	v_lshlrev_b32_e32 v54, 16, v55
	v_and_b32_e32 v55, 0xffff0000, v55
	v_lshlrev_b32_e32 v60, 16, v56
	v_and_b32_e32 v61, 0xffff0000, v56
	v_lshlrev_b32_e32 v56, 16, v57
	v_and_b32_e32 v57, 0xffff0000, v57
	v_pk_mul_f32 v[12:13], v[12:13], v[32:33]
	v_pk_mul_f32 v[6:7], v[6:7], v[54:55]
	v_pk_mul_f32 v[4:5], v[4:5], v[58:59]
	v_pk_mul_f32 v[16:17], v[16:17], v[30:31]
	v_pk_mul_f32 v[12:13], v[12:13], v[56:57]
	v_pk_mul_f32 v[16:17], v[16:17], v[60:61]
	v_cvt_pk_bf16_f32 v4, v4, v5
	v_cvt_pk_bf16_f32 v5, v6, v7
	s_nop 0
	v_cvt_pk_bf16_f32 v6, v16, v17
	v_cvt_pk_bf16_f32 v7, v12, v13
	v_lshl_add_u64 v[12:13], s[10:11], 0, v[20:21]
	v_add_co_u32_e32 v12, vcc, s0, v12
	s_add_u32 s10, s10, 0x4000
	s_nop 0
	v_addc_co_u32_e32 v13, vcc, 0, v13, vcc
	global_store_dwordx4 v[12:13], v[4:7], off
	s_nop 0
	s_nop 0
	s_nop 0
	s_nop 0
	s_nop 0
	s_nop 0
	s_addc_u32 s11, s11, 0
	s_add_u32 s14, s14, 0x38000
	v_add_co_u32_e32 v39, vcc, 8, v39
	s_addc_u32 s15, s15, 0
	s_and_b64 vcc, exec, vcc
	s_nop 0
	v_pk_fma_f32 v[4:5], v[214:215], v[14:15], v[222:223]
	v_pk_fma_f32 v[6:7], v[216:217], v[8:9], v[224:225]
	v_mul_f32_e32 v8, 0xbfb8aa3b, v4
	v_mul_f32_e32 v9, 0xbfb8aa3b, v5
	v_exp_f32_e32 v8, v8
	v_exp_f32_e32 v9, v9
	v_mul_f32_e32 v14, 0xbfb8aa3b, v6
	v_mul_f32_e32 v15, 0xbfb8aa3b, v7
	v_exp_f32_e32 v14, v14
	v_exp_f32_e32 v15, v15
	v_add_f32_e32 v8, 1.0, v8
	v_add_f32_e32 v9, 1.0, v9
	v_rcp_f32_e32 v8, v8
	v_rcp_f32_e32 v9, v9
	v_add_f32_e32 v14, 1.0, v14
	v_add_f32_e32 v15, 1.0, v15
	v_rcp_f32_e32 v14, v14
	v_rcp_f32_e32 v15, v15
	v_pk_mul_f32 v[4:5], v[4:5], v[8:9]
	v_pk_mul_f32 v[8:9], v[10:11], v[26:27] op_sel_hi:[1,0]
	v_pk_fma_f32 v[2:3], v[218:219], v[2:3], v[226:227]
	v_pk_fma_f32 v[8:9], v[220:221], v[8:9], v[228:229]
	v_pk_mul_f32 v[6:7], v[6:7], v[14:15]
	v_mul_f32_e32 v10, 0xbfb8aa3b, v2
	v_mul_f32_e32 v11, 0xbfb8aa3b, v3
	v_mul_f32_e32 v14, 0xbfb8aa3b, v8
	v_mul_f32_e32 v15, 0xbfb8aa3b, v9
	v_exp_f32_e32 v10, v10
	v_exp_f32_e32 v11, v11
	v_exp_f32_e32 v14, v14
	v_exp_f32_e32 v15, v15
	v_add_f32_e32 v10, 1.0, v10
	v_add_f32_e32 v11, 1.0, v11
	v_add_f32_e32 v14, 1.0, v14
	v_add_f32_e32 v15, 1.0, v15
	v_rcp_f32_e32 v10, v10
	v_rcp_f32_e32 v11, v11
	v_rcp_f32_e32 v14, v14
	v_rcp_f32_e32 v15, v15
	v_lshlrev_b32_e32 v16, 16, v230
	v_and_b32_e32 v17, 0xffff0000, v230
	v_lshlrev_b32_e32 v28, 16, v231
	v_and_b32_e32 v29, 0xffff0000, v231
	v_lshlrev_b32_e32 v50, 16, v232
	v_and_b32_e32 v51, 0xffff0000, v232
	v_lshlrev_b32_e32 v52, 16, v233
	v_and_b32_e32 v53, 0xffff0000, v233
	v_pk_mul_f32 v[4:5], v[4:5], v[16:17]
	v_pk_mul_f32 v[2:3], v[2:3], v[10:11]
	v_pk_mul_f32 v[8:9], v[8:9], v[14:15]
	v_pk_mul_f32 v[6:7], v[6:7], v[28:29]
	v_pk_mul_f32 v[8:9], v[8:9], v[52:53]
	v_pk_mul_f32 v[10:11], v[2:3], v[50:51]
	v_cvt_pk_bf16_f32 v2, v4, v5
	v_cvt_pk_bf16_f32 v3, v6, v7
	s_nop 0
	v_cvt_pk_bf16_f32 v4, v10, v11
	v_cvt_pk_bf16_f32 v5, v8, v9
	global_store_dwordx4 v[12:13], v[2:5], off offset:1024
	s_cbranch_vccnz .LBB0_635
	s_branch .LBB0_628
